# chain finish stages: 16-lane group-norm sums via DPP row reductions instead of four dependent ds_bpermute round trips
# baseline (speedup 1.0000x reference)
.LBB0_549:
	v_lshlrev_b32_e32 v0, 1, v131
	v_add_u32_e32 v1, v0, v118
	v_add_u32_e32 v1, 0x3400, v1
	v_mad_u32_u24 v131, v117, 40, v0
	ds_read2_b64 v[116:119], v1 offset0:64 offset1:144
	v_add_u32_e32 v143, v0, v0
	v_add_u32_e32 v1, 0x2000, v131
	ds_read2_b64 v[120:123], v1 offset0:64 offset1:144
	ds_read_b128 v[144:147], v143 offset:58880
	ds_read_b128 v[148:151], v143 offset:58944
	s_waitcnt lgkmcnt(3)
	v_mov_b32_e32 v0, v116
	v_add_u32_e32 v116, 0x2400, v131
	ds_read2_b64 v[152:155], v116 offset0:96 offset1:176
	v_add_u32_e32 v116, 0x2800, v131
	ds_read2_b64 v[168:171], v116 offset0:128 offset1:208
	v_add_u32_e32 v116, 0x3000, v131
	ds_read2_b64 v[184:187], v116 offset0:32 offset1:112
	ds_read_b128 v[160:163], v143 offset:59008
	ds_read_b128 v[164:167], v143 offset:59072
	ds_read_b128 v[176:179], v143 offset:59136
	ds_read_b128 v[180:183], v143 offset:59200
	ds_read_b128 v[208:211], v143 offset:59264
	ds_read_b128 v[214:217], v143 offset:59328
	s_waitcnt lgkmcnt(11)
	v_mov_b32_e32 v132, v120
	v_mov_b32_e32 v133, v121
	v_mov_b32_e32 v134, v2
	v_mov_b32_e32 v135, v2
	v_mov_b32_e32 v120, v122
	v_mov_b32_e32 v121, v123
	v_mov_b32_e32 v122, v2
	v_mov_b32_e32 v123, v2
	s_waitcnt lgkmcnt(8)
	v_mov_b32_e32 v156, v152
	v_mov_b32_e32 v157, v153
	v_mov_b32_e32 v158, v2
	v_mov_b32_e32 v159, v2
	v_mov_b32_e32 v152, v154
	v_mov_b32_e32 v153, v155
	v_mov_b32_e32 v154, v2
	v_mov_b32_e32 v155, v2
	s_waitcnt lgkmcnt(7)
	v_mov_b32_e32 v172, v168
	v_mov_b32_e32 v173, v169
	v_mov_b32_e32 v174, v2
	v_mov_b32_e32 v175, v2
	v_mov_b32_e32 v168, v170
	v_mov_b32_e32 v169, v171
	v_mov_b32_e32 v170, v2
	v_mov_b32_e32 v171, v2
	s_waitcnt lgkmcnt(6)
	v_mov_b32_e32 v188, v184
	v_mov_b32_e32 v189, v185
	v_mov_b32_e32 v190, v2
	v_mov_b32_e32 v191, v2
	v_mov_b32_e32 v184, v186
	v_mov_b32_e32 v185, v187
	v_mov_b32_e32 v186, v2
	v_mov_b32_e32 v187, v2
	v_mov_b32_e32 v1, v117
	v_mov_b32_e32 v3, v2
	v_pk_mul_f32 v[6:7], v[6:7], v[146:147]
	v_pk_mul_f32 v[4:5], v[4:5], v[144:145]
	v_pk_mul_f32 v[14:15], v[14:15], v[150:151]
	v_pk_mul_f32 v[12:13], v[12:13], v[148:149]
	s_waitcnt lgkmcnt(5)
	v_pk_mul_f32 v[22:23], v[22:23], v[162:163]
	v_pk_mul_f32 v[20:21], v[20:21], v[160:161]
	s_waitcnt lgkmcnt(4)
	v_pk_mul_f32 v[30:31], v[30:31], v[166:167]
	v_pk_mul_f32 v[28:29], v[28:29], v[164:165]
	s_waitcnt lgkmcnt(3)
	v_pk_mul_f32 v[38:39], v[38:39], v[178:179]
	v_pk_mul_f32 v[36:37], v[36:37], v[176:177]
	s_waitcnt lgkmcnt(2)
	v_pk_mul_f32 v[46:47], v[46:47], v[182:183]
	v_pk_mul_f32 v[44:45], v[44:45], v[180:181]
	s_waitcnt lgkmcnt(1)
	v_pk_mul_f32 v[54:55], v[54:55], v[210:211]
	v_pk_mul_f32 v[52:53], v[52:53], v[208:209]
	s_waitcnt lgkmcnt(0)
	v_pk_mul_f32 v[62:63], v[62:63], v[216:217]
	v_pk_mul_f32 v[60:61], v[60:61], v[214:215]
	v_mfma_f32_16x16x32_bf16 v[4:7], v[132:135], v[0:3], v[4:7]
	v_mul_f32_e64 v10, v10, v146
	v_mul_f32_e64 v11, v11, v147
	v_pk_mul_f32 v[8:9], v[8:9], v[144:145]
	v_pk_mul_f32 v[18:19], v[18:19], v[150:151]
	v_mfma_f32_16x16x32_bf16 v[12:15], v[120:123], v[0:3], v[12:15]
	v_mul_f32_e64 v16, v16, v148
	v_mul_f32_e64 v17, v17, v149
	v_pk_mul_f32 v[26:27], v[26:27], v[162:163]
	v_pk_mul_f32 v[24:25], v[24:25], v[160:161]
	v_mfma_f32_16x16x32_bf16 v[20:23], v[156:159], v[0:3], v[20:23]
	v_mul_f32_e64 v34, v34, v166
	v_mul_f32_e64 v35, v35, v167
	v_pk_mul_f32 v[32:33], v[32:33], v[164:165]
	v_pk_mul_f32 v[42:43], v[42:43], v[178:179]
	v_mfma_f32_16x16x32_bf16 v[28:31], v[152:155], v[0:3], v[28:31]
	v_mul_f32_e64 v40, v40, v176
	v_mul_f32_e64 v41, v41, v177
	v_pk_mul_f32 v[50:51], v[50:51], v[182:183]
	v_pk_mul_f32 v[48:49], v[48:49], v[180:181]
	v_mfma_f32_16x16x32_bf16 v[36:39], v[172:175], v[0:3], v[36:39]
	v_mul_f32_e64 v58, v58, v210
	v_mul_f32_e64 v59, v59, v211
	v_pk_mul_f32 v[56:57], v[56:57], v[208:209]
	v_pk_mul_f32 v[66:67], v[66:67], v[216:217]
	v_mfma_f32_16x16x32_bf16 v[44:47], v[168:171], v[0:3], v[44:47]
	v_mul_f32_e64 v64, v64, v214
	v_mul_f32_e64 v65, v65, v215
	s_and_b64 vcc, exec, s[38:39]
	v_mfma_f32_16x16x32_bf16 v[52:55], v[188:191], v[0:3], v[52:55]
	s_barrier
	v_mfma_f32_16x16x32_bf16 v[60:63], v[184:187], v[0:3], v[60:63]
	v_mov_b32_e32 v0, v118
	v_mov_b32_e32 v1, v119
	s_nop 1
	v_mfma_f32_16x16x32_bf16 v[8:11], v[132:135], v[0:3], v[8:11]
	v_mfma_f32_16x16x32_bf16 v[16:19], v[120:123], v[0:3], v[16:19]
	v_mfma_f32_16x16x32_bf16 v[24:27], v[156:159], v[0:3], v[24:27]
	v_mfma_f32_16x16x32_bf16 v[32:35], v[152:155], v[0:3], v[32:35]
	v_mfma_f32_16x16x32_bf16 v[40:43], v[172:175], v[0:3], v[40:43]
	v_mfma_f32_16x16x32_bf16 v[48:51], v[168:171], v[0:3], v[48:51]
	v_mfma_f32_16x16x32_bf16 v[56:59], v[188:191], v[0:3], v[56:59]
	v_mfma_f32_16x16x32_bf16 v[64:67], v[184:187], v[0:3], v[64:67]
	s_cbranch_vccnz .LBB0_553
	s_movk_i32 s0, 0x410
	v_mul_lo_u32 v0, v139, s0
	v_lshl_add_u32 v0, v138, 2, v0
	ds_read_b128 v[120:123], v0 offset:24064
	ds_read_b128 v[116:119], v0 offset:24080
	v_xor_b32_e32 v3, 8, v202
	s_waitcnt lgkmcnt(1)
	v_pk_mul_f32 v[0:1], v[120:121], v[120:121]
	v_pk_mul_f32 v[132:133], v[122:123], v[122:123]
	v_add_f32_e32 v0, v0, v1
	v_add_f32_e32 v0, v0, v132
	s_waitcnt lgkmcnt(0)
	v_pk_mul_f32 v[134:135], v[116:117], v[116:117]
	v_add_f32_e32 v0, v0, v133
	v_and_b32_e32 v1, 64, v202
	v_add_f32_e32 v0, v0, v134
	v_add_u32_e32 v1, 64, v1
	v_pk_mul_f32 v[144:145], v[118:119], v[118:119]
	v_add_f32_e32 v0, v0, v135
	v_cmp_lt_i32_e32 vcc, v3, v1
	v_add_f32_e32 v0, v0, v144
	v_add_f32_e32 v0, v0, v145
	v_cndmask_b32_e32 v3, v202, v3, vcc
	v_lshlrev_b32_e32 v3, 2, v3
	s_waitcnt lgkmcnt(0)
	v_xor_b32_e32 v3, 4, v202
	v_cmp_lt_i32_e32 vcc, v3, v1
	s_nop 1
	v_cndmask_b32_e32 v3, v202, v3, vcc
	v_lshlrev_b32_e32 v3, 2, v3
	s_waitcnt lgkmcnt(0)
	v_xor_b32_e32 v3, 2, v202
	v_cmp_lt_i32_e32 vcc, v3, v1
	s_nop 1
	v_cndmask_b32_e32 v3, v202, v3, vcc
	v_lshlrev_b32_e32 v3, 2, v3
	s_waitcnt lgkmcnt(0)
	v_xor_b32_e32 v3, 1, v202
	v_cmp_lt_i32_e32 vcc, v3, v1
	s_nop 1
	v_cndmask_b32_e32 v1, v202, v3, vcc
	v_lshlrev_b32_e32 v1, 2, v1
	s_nop 1
	v_add_f32_dpp v0, v0, v0 quad_perm:[1,0,3,2] row_mask:0xf bank_mask:0xf
	s_nop 1
	v_add_f32_dpp v0, v0, v0 quad_perm:[2,3,0,1] row_mask:0xf bank_mask:0xf
	s_nop 1
	v_add_f32_dpp v0, v0, v0 row_half_mirror row_mask:0xf bank_mask:0xf
	s_nop 1
	v_add_f32_dpp v0, v0, v0 row_mirror row_mask:0xf bank_mask:0xf
	s_nop 1
	v_mov_b32_e32 v1, 0
	v_cmp_gt_i32_e32 vcc, s52, v139
	s_and_saveexec_b64 s[0:1], vcc
	s_cbranch_execz .LBB0_552
	s_waitcnt lgkmcnt(0)
	v_add_f32_e32 v0, v0, v1
	v_fmamk_f32 v0, v0, 0x3c000000, v198
	s_mov_b32 s4, 0x800000
	v_cmp_gt_f32_e32 vcc, s4, v0
	v_mul_f32_e32 v1, 0x4b800000, v0
	v_add_u32_e32 v132, s49, v139
	v_cndmask_b32_e32 v0, v0, v1, vcc
	v_rsq_f32_e32 v0, v0
	v_ashrrev_i32_e32 v133, 31, v132
	v_mov_b32_e32 v139, v2
	v_mul_f32_e32 v1, 0x45800000, v0
	v_cndmask_b32_e32 v0, v0, v1, vcc
	v_lshlrev_b32_e32 v1, 16, v88
	v_mul_f32_e32 v1, 0xbfb8aa3b, v1
	v_exp_f32_e32 v1, v1
	s_nop 0
	v_add_f32_e32 v1, 1.0, v1
	v_rcp_f32_e32 v134, v1
	v_and_b32_e32 v1, 0xffff0000, v88
	v_mul_f32_e32 v1, 0xbfb8aa3b, v1
	v_exp_f32_e32 v1, v1
	s_nop 0
	v_add_f32_e32 v1, 1.0, v1
	v_rcp_f32_e32 v135, v1
	v_pk_mul_f32 v[120:121], v[120:121], v[0:1] op_sel_hi:[1,0]
	v_lshlrev_b32_e32 v1, 16, v89
	v_mul_f32_e32 v1, 0xbfb8aa3b, v1
	v_exp_f32_e32 v1, v1
	v_pk_mul_f32 v[120:121], v[76:77], v[120:121]
	v_add_f32_e32 v1, 1.0, v1
	v_rcp_f32_e32 v88, v1
	v_and_b32_e32 v1, 0xffff0000, v89
	v_mul_f32_e32 v1, 0xbfb8aa3b, v1
	v_exp_f32_e32 v1, v1
	v_pk_mul_f32 v[120:121], v[134:135], v[120:121]
	v_add_f32_e32 v1, 1.0, v1
	v_rcp_f32_e32 v89, v1
	v_pk_mul_f32 v[122:123], v[122:123], v[0:1] op_sel_hi:[1,0]
	v_lshlrev_b32_e32 v1, 16, v90
	v_mul_f32_e32 v1, 0xbfb8aa3b, v1
	v_exp_f32_e32 v1, v1
	v_pk_mul_f32 v[122:123], v[78:79], v[122:123]
	v_add_f32_e32 v1, 1.0, v1
	v_pk_mul_f32 v[122:123], v[88:89], v[122:123]
	v_rcp_f32_e32 v88, v1
	v_and_b32_e32 v1, 0xffff0000, v90
	v_mul_f32_e32 v1, 0xbfb8aa3b, v1
	v_exp_f32_e32 v1, v1
	s_nop 0
	v_add_f32_e32 v1, 1.0, v1
	v_rcp_f32_e32 v89, v1
	v_pk_mul_f32 v[116:117], v[116:117], v[0:1] op_sel_hi:[1,0]
	v_lshlrev_b32_e32 v1, 16, v91
	v_mul_f32_e32 v1, 0xbfb8aa3b, v1
	v_exp_f32_e32 v1, v1
	v_pk_mul_f32 v[116:117], v[72:73], v[116:117]
	v_add_f32_e32 v1, 1.0, v1
	v_pk_mul_f32 v[116:117], v[88:89], v[116:117]
	v_rcp_f32_e32 v88, v1
	v_and_b32_e32 v1, 0xffff0000, v91
	v_mul_f32_e32 v1, 0xbfb8aa3b, v1
	v_exp_f32_e32 v1, v1
	v_cvt_pk_bf16_f32 v90, v116, v117
	v_lshl_add_u64 v[116:117], v[138:139], 0, s[42:43]
	v_add_f32_e32 v1, 1.0, v1
	v_rcp_f32_e32 v89, v1
	v_pk_mul_f32 v[0:1], v[118:119], v[0:1] op_sel_hi:[1,0]
	s_nop 0
	v_pk_mul_f32 v[0:1], v[74:75], v[0:1]
	s_nop 0
	v_pk_mul_f32 v[0:1], v[88:89], v[0:1]
	v_cvt_pk_bf16_f32 v88, v120, v121
	v_cvt_pk_bf16_f32 v91, v0, v1
	v_lshlrev_b64 v[0:1], 12, v[132:133]
	v_lshl_add_u64 v[0:1], s[80:81], 0, v[0:1]
	v_cvt_pk_bf16_f32 v89, v122, v123
	v_lshl_add_u64 v[0:1], v[116:117], 1, v[0:1]
	global_store_dwordx4 v[0:1], v[88:91], off offset:2048

.LBB0_818:
	v_lshlrev_b32_e32 v1, 1, v171
	v_lshlrev_b32_e32 v0, 2, v165
	v_mad_u32_u24 v188, v155, 40, v1
	v_add_u32_e32 v1, v1, v164
	ds_read_b32 v0, v0 offset:59392
	v_add_u32_e32 v1, 0x4800, v1
	ds_read2_b64 v[132:135], v1 offset0:64 offset1:144
	v_add_u32_e32 v1, 0x2000, v188
	ds_read2_b64 v[164:167], v1 offset0:64 offset1:144
	s_waitcnt lgkmcnt(2)
	v_mul_f32_e32 v0, 0x3fb8aa3b, v0
	v_exp_f32_e32 v152, v0
	s_waitcnt lgkmcnt(1)
	v_mov_b32_e32 v0, v132
	v_add_u32_e32 v132, 0x2400, v188
	ds_read2_b64 v[172:175], v132 offset0:96 offset1:176
	v_add_u32_e32 v132, 0x2800, v188
	ds_read2_b64 v[180:183], v132 offset0:128 offset1:208
	v_add_u32_e32 v132, 0x3000, v188
	ds_read2_b64 v[188:191], v132 offset0:32 offset1:112
	s_waitcnt lgkmcnt(3)
	v_mov_b32_e32 v168, v164
	v_mov_b32_e32 v169, v165
	v_mov_b32_e32 v170, v2
	v_mov_b32_e32 v171, v2
	v_mov_b32_e32 v164, v166
	v_mov_b32_e32 v165, v167
	v_mov_b32_e32 v166, v2
	v_mov_b32_e32 v167, v2
	s_waitcnt lgkmcnt(2)
	v_mov_b32_e32 v176, v172
	v_mov_b32_e32 v177, v173
	v_mov_b32_e32 v178, v2
	v_mov_b32_e32 v179, v2
	v_mov_b32_e32 v172, v174
	v_mov_b32_e32 v173, v175
	v_mov_b32_e32 v174, v2
	v_mov_b32_e32 v175, v2
	s_waitcnt lgkmcnt(1)
	v_mov_b32_e32 v184, v180
	v_mov_b32_e32 v185, v181
	v_mov_b32_e32 v186, v2
	v_mov_b32_e32 v187, v2
	v_mov_b32_e32 v180, v182
	v_mov_b32_e32 v181, v183
	v_mov_b32_e32 v182, v2
	v_mov_b32_e32 v183, v2
	s_waitcnt lgkmcnt(0)
	v_mov_b32_e32 v208, v188
	v_mov_b32_e32 v209, v189
	v_mov_b32_e32 v210, v2
	v_mov_b32_e32 v211, v2
	v_mov_b32_e32 v188, v190
	v_mov_b32_e32 v189, v191
	v_mov_b32_e32 v190, v2
	v_mov_b32_e32 v191, v2
	v_mov_b32_e32 v1, v133
	v_mov_b32_e32 v3, v2
	v_pk_mul_f32 v[6:7], v[6:7], v[152:153] op_sel_hi:[1,0]
	v_pk_mul_f32 v[4:5], v[4:5], v[152:153] op_sel_hi:[1,0]
	v_pk_mul_f32 v[14:15], v[14:15], v[152:153] op_sel_hi:[1,0]
	v_pk_mul_f32 v[12:13], v[12:13], v[152:153] op_sel_hi:[1,0]
	v_pk_mul_f32 v[22:23], v[22:23], v[152:153] op_sel_hi:[1,0]
	v_pk_mul_f32 v[20:21], v[20:21], v[152:153] op_sel_hi:[1,0]
	v_pk_mul_f32 v[30:31], v[30:31], v[152:153] op_sel_hi:[1,0]
	v_pk_mul_f32 v[28:29], v[28:29], v[152:153] op_sel_hi:[1,0]
	v_pk_mul_f32 v[38:39], v[38:39], v[152:153] op_sel_hi:[1,0]
	v_pk_mul_f32 v[36:37], v[36:37], v[152:153] op_sel_hi:[1,0]
	v_pk_mul_f32 v[46:47], v[46:47], v[152:153] op_sel_hi:[1,0]
	v_pk_mul_f32 v[44:45], v[44:45], v[152:153] op_sel_hi:[1,0]
	v_pk_mul_f32 v[54:55], v[54:55], v[152:153] op_sel_hi:[1,0]
	v_pk_mul_f32 v[52:53], v[52:53], v[152:153] op_sel_hi:[1,0]
	v_pk_mul_f32 v[62:63], v[62:63], v[152:153] op_sel_hi:[1,0]
	v_pk_mul_f32 v[60:61], v[60:61], v[152:153] op_sel_hi:[1,0]
	v_mfma_f32_16x16x32_bf16 v[4:7], v[168:171], v[0:3], v[4:7]
	v_mul_f32_e64 v10, v10, v152
	v_mul_f32_e64 v11, v11, v152
	v_pk_mul_f32 v[8:9], v[8:9], v[152:153] op_sel_hi:[1,0]
	v_pk_mul_f32 v[18:19], v[18:19], v[152:153] op_sel_hi:[1,0]
	v_mfma_f32_16x16x32_bf16 v[12:15], v[164:167], v[0:3], v[12:15]
	v_mul_f32_e64 v16, v16, v152
	v_mul_f32_e64 v17, v17, v152
	v_pk_mul_f32 v[26:27], v[26:27], v[152:153] op_sel_hi:[1,0]
	v_pk_mul_f32 v[24:25], v[24:25], v[152:153] op_sel_hi:[1,0]
	v_mfma_f32_16x16x32_bf16 v[20:23], v[176:179], v[0:3], v[20:23]
	v_mul_f32_e64 v34, v34, v152
	v_mul_f32_e64 v35, v35, v152
	v_pk_mul_f32 v[32:33], v[32:33], v[152:153] op_sel_hi:[1,0]
	v_pk_mul_f32 v[42:43], v[42:43], v[152:153] op_sel_hi:[1,0]
	v_mfma_f32_16x16x32_bf16 v[28:31], v[172:175], v[0:3], v[28:31]
	v_mul_f32_e64 v40, v40, v152
	v_mul_f32_e64 v41, v41, v152
	v_pk_mul_f32 v[50:51], v[50:51], v[152:153] op_sel_hi:[1,0]
	v_pk_mul_f32 v[48:49], v[48:49], v[152:153] op_sel_hi:[1,0]
	v_mfma_f32_16x16x32_bf16 v[36:39], v[184:187], v[0:3], v[36:39]
	v_mul_f32_e64 v58, v58, v152
	v_mul_f32_e64 v59, v59, v152
	v_pk_mul_f32 v[56:57], v[56:57], v[152:153] op_sel_hi:[1,0]
	v_pk_mul_f32 v[66:67], v[66:67], v[152:153] op_sel_hi:[1,0]
	v_mfma_f32_16x16x32_bf16 v[44:47], v[180:183], v[0:3], v[44:47]
	v_mul_f32_e64 v64, v64, v152
	v_mul_f32_e64 v65, v65, v152
	s_andn2_b64 vcc, exec, s[40:41]
	v_mfma_f32_16x16x32_bf16 v[52:55], v[208:211], v[0:3], v[52:55]
	s_barrier
	v_mfma_f32_16x16x32_bf16 v[60:63], v[188:191], v[0:3], v[60:63]
	v_mov_b32_e32 v0, v134
	v_mov_b32_e32 v1, v135
	s_nop 1
	v_mfma_f32_16x16x32_bf16 v[8:11], v[168:171], v[0:3], v[8:11]
	v_mfma_f32_16x16x32_bf16 v[16:19], v[164:167], v[0:3], v[16:19]
	v_mfma_f32_16x16x32_bf16 v[24:27], v[176:179], v[0:3], v[24:27]
	v_mfma_f32_16x16x32_bf16 v[32:35], v[172:175], v[0:3], v[32:35]
	v_mfma_f32_16x16x32_bf16 v[40:43], v[184:187], v[0:3], v[40:43]
	v_mfma_f32_16x16x32_bf16 v[48:51], v[180:183], v[0:3], v[48:51]
	v_mfma_f32_16x16x32_bf16 v[56:59], v[208:211], v[0:3], v[56:59]
	v_mfma_f32_16x16x32_bf16 v[64:67], v[188:191], v[0:3], v[64:67]
	s_cbranch_vccnz .LBB0_824
	s_movk_i32 s3, 0x410
	v_mul_lo_u32 v0, v154, s3
	v_lshl_add_u32 v3, v137, 2, v0
	v_lshlrev_b32_e32 v0, 16, v80
	v_and_b32_e32 v1, 0xffff0000, v80
	v_mul_f32_e32 v80, 0xbfb8aa3b, v0
	v_exp_f32_e32 v80, v80
	ds_read_b128 v[132:135], v3 offset:24064
	ds_read_b128 v[164:167], v3 offset:24080
	ds_read_b128 v[168:171], v153 offset:53248
	v_mul_f32_e32 v3, 0xbfb8aa3b, v1
	v_exp_f32_e32 v3, v3
	v_add_f32_e32 v80, 1.0, v80
	v_rcp_f32_e32 v152, v80
	v_lshlrev_b32_e32 v80, 16, v81
	v_add_f32_e32 v3, 1.0, v3
	v_rcp_f32_e32 v153, v3
	v_mul_f32_e32 v3, 0xbfb8aa3b, v80
	v_exp_f32_e32 v3, v3
	v_and_b32_e32 v81, 0xffff0000, v81
	v_pk_mul_f32 v[0:1], v[152:153], v[0:1]
	s_waitcnt lgkmcnt(0)
	v_and_b32_e32 v173, 0xffff0000, v168
	v_add_f32_e32 v3, 1.0, v3
	v_rcp_f32_e32 v152, v3
	v_mul_f32_e32 v3, 0xbfb8aa3b, v81
	v_exp_f32_e32 v3, v3
	v_lshlrev_b32_e32 v172, 16, v168
	v_pk_fma_f32 v[132:133], v[146:147], v[172:173], v[132:133]
	v_and_b32_e32 v173, 0xffff0000, v169
	v_add_f32_e32 v3, 1.0, v3
	v_rcp_f32_e32 v153, v3
	v_lshlrev_b32_e32 v172, 16, v169
	v_pk_mul_f32 v[0:1], v[0:1], v[132:133]
	v_pk_fma_f32 v[134:135], v[146:147], v[172:173], v[134:135]
	v_pk_mul_f32 v[80:81], v[152:153], v[80:81]
	v_lshlrev_b32_e32 v152, 16, v82
	v_mul_f32_e32 v3, 0xbfb8aa3b, v152
	v_exp_f32_e32 v3, v3
	v_and_b32_e32 v153, 0xffff0000, v82
	v_lshlrev_b32_e32 v82, 16, v83
	v_and_b32_e32 v83, 0xffff0000, v83
	v_add_f32_e32 v3, 1.0, v3
	v_rcp_f32_e32 v168, v3
	v_mul_f32_e32 v3, 0xbfb8aa3b, v153
	v_exp_f32_e32 v3, v3
	v_pk_mul_f32 v[132:133], v[0:1], v[0:1]
	v_pk_mul_f32 v[80:81], v[80:81], v[134:135]
	v_and_b32_e32 v173, 0xffff0000, v170
	v_add_f32_e32 v3, 1.0, v3
	v_rcp_f32_e32 v169, v3
	v_mul_f32_e32 v3, 0xbfb8aa3b, v82
	v_exp_f32_e32 v3, v3
	v_lshlrev_b32_e32 v172, 16, v170
	v_pk_mul_f32 v[152:153], v[168:169], v[152:153]
	v_pk_mul_f32 v[134:135], v[80:81], v[80:81]
	v_add_f32_e32 v3, 1.0, v3
	v_rcp_f32_e32 v168, v3
	v_mul_f32_e32 v3, 0xbfb8aa3b, v83
	v_exp_f32_e32 v3, v3
	v_pk_fma_f32 v[164:165], v[146:147], v[172:173], v[164:165]
	v_and_b32_e32 v173, 0xffff0000, v171
	v_pk_mul_f32 v[152:153], v[152:153], v[164:165]
	v_add_f32_e32 v3, 1.0, v3
	v_rcp_f32_e32 v169, v3
	v_add_f32_e32 v3, v132, v133
	v_lshlrev_b32_e32 v172, 16, v171
	v_add_f32_e32 v3, v3, v134
	v_pk_mul_f32 v[164:165], v[152:153], v[152:153]
	v_pk_fma_f32 v[166:167], v[146:147], v[172:173], v[166:167]
	v_pk_mul_f32 v[82:83], v[168:169], v[82:83]
	v_add_f32_e32 v3, v3, v135
	v_and_b32_e32 v132, 64, v202
	v_pk_mul_f32 v[82:83], v[82:83], v[166:167]
	v_add_f32_e32 v3, v3, v164
	v_add_u32_e32 v132, 64, v132
	v_xor_b32_e32 v133, 8, v202
	v_pk_mul_f32 v[166:167], v[82:83], v[82:83]
	v_add_f32_e32 v3, v3, v165
	v_cmp_lt_i32_e32 vcc, v133, v132
	v_add_f32_e32 v3, v3, v166
	v_add_f32_e32 v3, v3, v167
	v_cndmask_b32_e32 v133, v202, v133, vcc
	v_lshlrev_b32_e32 v133, 2, v133
	s_min_i32 s2, s26, 16
	s_waitcnt lgkmcnt(0)
	v_xor_b32_e32 v133, 4, v202
	v_cmp_lt_i32_e32 vcc, v133, v132
	s_nop 1
	v_cndmask_b32_e32 v133, v202, v133, vcc
	v_lshlrev_b32_e32 v133, 2, v133
	s_waitcnt lgkmcnt(0)
	v_xor_b32_e32 v133, 2, v202
	v_cmp_lt_i32_e32 vcc, v133, v132
	s_nop 1
	v_cndmask_b32_e32 v133, v202, v133, vcc
	v_lshlrev_b32_e32 v133, 2, v133
	s_waitcnt lgkmcnt(0)
	v_xor_b32_e32 v133, 1, v202
	v_cmp_lt_i32_e32 vcc, v133, v132
	s_nop 1
	v_cndmask_b32_e32 v132, v202, v133, vcc
	v_lshlrev_b32_e32 v132, 2, v132
	s_nop 1
	v_add_f32_dpp v3, v3, v3 quad_perm:[1,0,3,2] row_mask:0xf bank_mask:0xf
	s_nop 1
	v_add_f32_dpp v3, v3, v3 quad_perm:[2,3,0,1] row_mask:0xf bank_mask:0xf
	s_nop 1
	v_add_f32_dpp v3, v3, v3 row_half_mirror row_mask:0xf bank_mask:0xf
	s_nop 1
	v_add_f32_dpp v3, v3, v3 row_mirror row_mask:0xf bank_mask:0xf
	s_nop 1
	v_mov_b32_e32 v164, 0
	v_cmp_gt_i32_e32 vcc, s2, v154
	s_and_saveexec_b64 s[2:3], vcc
	s_cbranch_execz .LBB0_823
	s_add_i32 s97, s97, s20
	v_add_u32_e32 v154, s97, v154
	v_cmp_eq_u32_e32 vcc, 0, v155
	v_ashrrev_i32_e32 v155, 31, v154
	s_and_saveexec_b64 s[30:31], vcc
	s_cbranch_execz .LBB0_822
	s_waitcnt lgkmcnt(0)
	v_add_f32_e32 v3, v3, v164
	v_lshl_add_u64 v[132:133], v[154:155], 4, s[8:9]
	global_store_dword v[132:133], v3, off

.LBB0_927:
	v_cvt_f32_i32_e32 v0, s3
	v_lshlrev_b32_e32 v1, 1, v148
	v_mad_u32_u24 v166, v127, 40, v1
	v_add_u32_e32 v1, v1, v123
	v_mul_f32_e32 v0, v119, v0
	v_mul_f32_e32 v0, 0x3fb8aa3b, v0
	v_exp_f32_e32 v122, v0
	v_add_u32_e32 v1, 0x3400, v1
	ds_read2_b64 v[126:129], v1 offset0:64 offset1:144
	v_add_u32_e32 v1, 0x2000, v166
	v_pk_mul_f32 v[6:7], v[6:7], v[122:123] op_sel_hi:[1,0]
	v_pk_mul_f32 v[4:5], v[4:5], v[122:123] op_sel_hi:[1,0]
	v_add_u32_e32 v123, 0x2400, v166
	ds_read2_b64 v[150:153], v123 offset0:96 offset1:176
	v_pk_mul_f32 v[14:15], v[14:15], v[122:123] op_sel_hi:[1,0]
	v_pk_mul_f32 v[12:13], v[12:13], v[122:123] op_sel_hi:[1,0]
	v_pk_mul_f32 v[22:23], v[22:23], v[122:123] op_sel_hi:[1,0]
	v_pk_mul_f32 v[20:21], v[20:21], v[122:123] op_sel_hi:[1,0]
	v_add_u32_e32 v123, 0x2800, v166
	ds_read2_b64 v[158:161], v123 offset0:128 offset1:208
	v_pk_mul_f32 v[30:31], v[30:31], v[122:123] op_sel_hi:[1,0]
	v_pk_mul_f32 v[28:29], v[28:29], v[122:123] op_sel_hi:[1,0]
	v_pk_mul_f32 v[38:39], v[38:39], v[122:123] op_sel_hi:[1,0]
	v_pk_mul_f32 v[36:37], v[36:37], v[122:123] op_sel_hi:[1,0]
	v_add_u32_e32 v123, 0x3000, v166
	ds_read2_b64 v[132:135], v1 offset0:64 offset1:144
	ds_read2_b64 v[166:169], v123 offset0:32 offset1:112
	v_mov_b32_e32 v148, v2
	v_mov_b32_e32 v149, v2
	s_waitcnt lgkmcnt(3)
	v_mov_b32_e32 v154, v150
	s_waitcnt lgkmcnt(1)
	v_mov_b32_e32 v146, v132
	v_mov_b32_e32 v147, v133
	v_mov_b32_e32 v132, v134
	v_mov_b32_e32 v133, v135
	v_mov_b32_e32 v134, v2
	v_mov_b32_e32 v135, v2
	v_mov_b32_e32 v155, v151
	v_mov_b32_e32 v156, v2
	v_mov_b32_e32 v157, v2
	v_mov_b32_e32 v150, v152
	v_mov_b32_e32 v151, v153
	v_mov_b32_e32 v152, v2
	v_mov_b32_e32 v153, v2
	v_mov_b32_e32 v162, v158
	v_mov_b32_e32 v163, v159
	v_mov_b32_e32 v164, v2
	v_mov_b32_e32 v165, v2
	v_mov_b32_e32 v158, v160
	v_mov_b32_e32 v159, v161
	v_mov_b32_e32 v160, v2
	v_mov_b32_e32 v161, v2
	s_waitcnt lgkmcnt(0)
	v_mov_b32_e32 v170, v166
	v_mov_b32_e32 v171, v167
	v_mov_b32_e32 v172, v2
	v_mov_b32_e32 v173, v2
	v_mov_b32_e32 v166, v168
	v_mov_b32_e32 v167, v169
	v_mov_b32_e32 v168, v2
	v_mov_b32_e32 v169, v2
	v_mov_b32_e32 v0, v126
	v_mov_b32_e32 v1, v127
	v_mov_b32_e32 v3, v2
	v_pk_mul_f32 v[46:47], v[46:47], v[122:123] op_sel_hi:[1,0]
	v_pk_mul_f32 v[44:45], v[44:45], v[122:123] op_sel_hi:[1,0]
	v_pk_mul_f32 v[54:55], v[54:55], v[122:123] op_sel_hi:[1,0]
	v_pk_mul_f32 v[52:53], v[52:53], v[122:123] op_sel_hi:[1,0]
	v_pk_mul_f32 v[62:63], v[62:63], v[122:123] op_sel_hi:[1,0]
	v_pk_mul_f32 v[60:61], v[60:61], v[122:123] op_sel_hi:[1,0]
	v_mfma_f32_16x16x32_bf16 v[4:7], v[146:149], v[0:3], v[4:7]
	v_mul_f32_e64 v10, v10, v122
	v_mul_f32_e64 v11, v11, v122
	v_pk_mul_f32 v[8:9], v[8:9], v[122:123] op_sel_hi:[1,0]
	v_pk_mul_f32 v[18:19], v[18:19], v[122:123] op_sel_hi:[1,0]
	v_mfma_f32_16x16x32_bf16 v[12:15], v[132:135], v[0:3], v[12:15]
	v_mul_f32_e64 v16, v16, v122
	v_mul_f32_e64 v17, v17, v122
	v_pk_mul_f32 v[26:27], v[26:27], v[122:123] op_sel_hi:[1,0]
	v_pk_mul_f32 v[24:25], v[24:25], v[122:123] op_sel_hi:[1,0]
	v_mfma_f32_16x16x32_bf16 v[20:23], v[154:157], v[0:3], v[20:23]
	v_mul_f32_e64 v34, v34, v122
	v_mul_f32_e64 v35, v35, v122
	v_pk_mul_f32 v[32:33], v[32:33], v[122:123] op_sel_hi:[1,0]
	v_pk_mul_f32 v[42:43], v[42:43], v[122:123] op_sel_hi:[1,0]
	v_mfma_f32_16x16x32_bf16 v[28:31], v[150:153], v[0:3], v[28:31]
	v_mul_f32_e64 v40, v40, v122
	v_mul_f32_e64 v41, v41, v122
	v_pk_mul_f32 v[50:51], v[50:51], v[122:123] op_sel_hi:[1,0]
	v_pk_mul_f32 v[48:49], v[48:49], v[122:123] op_sel_hi:[1,0]
	v_mfma_f32_16x16x32_bf16 v[36:39], v[162:165], v[0:3], v[36:39]
	v_mul_f32_e64 v58, v58, v122
	v_mul_f32_e64 v59, v59, v122
	v_pk_mul_f32 v[56:57], v[56:57], v[122:123] op_sel_hi:[1,0]
	v_pk_mul_f32 v[66:67], v[66:67], v[122:123] op_sel_hi:[1,0]
	v_mfma_f32_16x16x32_bf16 v[44:47], v[158:161], v[0:3], v[44:47]
	v_mul_f32_e64 v64, v64, v122
	v_mul_f32_e64 v65, v65, v122
	s_and_b64 vcc, exec, s[38:39]
	v_mfma_f32_16x16x32_bf16 v[52:55], v[170:173], v[0:3], v[52:55]
	s_barrier
	v_mfma_f32_16x16x32_bf16 v[60:63], v[166:169], v[0:3], v[60:63]
	v_mov_b32_e32 v0, v128
	v_mov_b32_e32 v1, v129
	s_nop 1
	v_mfma_f32_16x16x32_bf16 v[8:11], v[146:149], v[0:3], v[8:11]
	v_mfma_f32_16x16x32_bf16 v[16:19], v[132:135], v[0:3], v[16:19]
	v_mfma_f32_16x16x32_bf16 v[24:27], v[154:157], v[0:3], v[24:27]
	v_mfma_f32_16x16x32_bf16 v[32:35], v[150:153], v[0:3], v[32:35]
	v_mfma_f32_16x16x32_bf16 v[40:43], v[162:165], v[0:3], v[40:43]
	v_mfma_f32_16x16x32_bf16 v[48:51], v[158:161], v[0:3], v[48:51]
	v_mfma_f32_16x16x32_bf16 v[56:59], v[170:173], v[0:3], v[56:59]
	v_mfma_f32_16x16x32_bf16 v[64:67], v[166:169], v[0:3], v[64:67]
	s_cbranch_vccnz .LBB0_931
	s_movk_i32 s5, 0x410
	v_mul_lo_u32 v0, v145, s5
	v_lshl_add_u32 v0, v140, 2, v0
	ds_read_b128 v[132:135], v0 offset:24064
	ds_read_b128 v[146:149], v0 offset:24080
	v_and_b32_e32 v1, 64, v202
	v_add_u32_e32 v1, 64, v1
	v_xor_b32_e32 v3, 8, v202
	s_waitcnt lgkmcnt(1)
	v_add_f32_e32 v0, 0, v132
	v_add_f32_e32 v0, v0, v133
	v_add_f32_e32 v0, v0, v134
	v_add_f32_e32 v0, v0, v135
	s_waitcnt lgkmcnt(0)
	v_add_f32_e32 v0, v0, v146
	v_cmp_lt_i32_e32 vcc, v3, v1
	v_add_f32_e32 v0, v0, v147
	v_add_f32_e32 v0, v0, v148
	v_cndmask_b32_e32 v3, v202, v3, vcc
	v_lshlrev_b32_e32 v3, 2, v3
	v_add_f32_e32 v0, v0, v149
	v_xor_b32_e32 v123, 4, v202
	v_cmp_lt_i32_e32 vcc, v123, v1
	s_waitcnt lgkmcnt(0)
	v_cndmask_b32_e32 v123, v202, v123, vcc
	v_lshlrev_b32_e32 v150, 2, v123
	v_xor_b32_e32 v123, 2, v202
	v_cmp_lt_i32_e32 vcc, v123, v1
	s_waitcnt lgkmcnt(0)
	v_cndmask_b32_e32 v123, v202, v123, vcc
	v_lshlrev_b32_e32 v151, 2, v123
	v_xor_b32_e32 v123, 1, v202
	v_cmp_lt_i32_e32 vcc, v123, v1
	s_waitcnt lgkmcnt(0)
	v_cndmask_b32_e32 v1, v202, v123, vcc
	v_lshlrev_b32_e32 v152, 2, v1
	s_nop 1
	v_add_f32_dpp v0, v0, v0 quad_perm:[1,0,3,2] row_mask:0xf bank_mask:0xf
	s_nop 1
	v_add_f32_dpp v0, v0, v0 quad_perm:[2,3,0,1] row_mask:0xf bank_mask:0xf
	s_nop 1
	v_add_f32_dpp v0, v0, v0 row_half_mirror row_mask:0xf bank_mask:0xf
	s_nop 1
	v_add_f32_dpp v0, v0, v0 row_mirror row_mask:0xf bank_mask:0xf
	s_nop 1
	v_mov_b32_e32 v1, 0
	v_cmp_gt_i32_e32 vcc, s3, v145
	s_waitcnt lgkmcnt(0)
	v_add_f32_e32 v0, v0, v1
	v_mul_f32_e32 v0, 0x3c000000, v0
	v_pk_add_f32 v[128:129], v[132:133], v[0:1] op_sel_hi:[1,0] neg_lo:[0,1] neg_hi:[0,1]
	v_pk_add_f32 v[126:127], v[134:135], v[0:1] op_sel_hi:[1,0] neg_lo:[0,1] neg_hi:[0,1]
	v_pk_mul_f32 v[132:133], v[128:129], v[128:129]
	v_pk_mul_f32 v[134:135], v[126:127], v[126:127]
	v_add_f32_e32 v132, v132, v133
	v_pk_add_f32 v[122:123], v[146:147], v[0:1] op_sel_hi:[1,0] neg_lo:[0,1] neg_hi:[0,1]
	v_add_f32_e32 v132, v134, v132
	v_pk_mul_f32 v[146:147], v[122:123], v[122:123]
	v_add_f32_e32 v132, v135, v132
	v_pk_add_f32 v[0:1], v[148:149], v[0:1] op_sel_hi:[1,0] neg_lo:[0,1] neg_hi:[0,1]
	v_add_f32_e32 v132, v146, v132
	v_pk_mul_f32 v[148:149], v[0:1], v[0:1]
	v_add_f32_e32 v132, v147, v132
	v_add_f32_e32 v132, v148, v132
	v_add_f32_e32 v132, v149, v132
	v_mov_b32_e32 v3, v132
	s_waitcnt lgkmcnt(0)
	s_waitcnt lgkmcnt(0)
	s_waitcnt lgkmcnt(0)
	s_nop 1
	v_add_f32_dpp v3, v3, v3 quad_perm:[1,0,3,2] row_mask:0xf bank_mask:0xf
	s_nop 1
	v_add_f32_dpp v3, v3, v3 quad_perm:[2,3,0,1] row_mask:0xf bank_mask:0xf
	s_nop 1
	v_add_f32_dpp v3, v3, v3 row_half_mirror row_mask:0xf bank_mask:0xf
	s_nop 1
	v_add_f32_dpp v3, v3, v3 row_mirror row_mask:0xf bank_mask:0xf
	s_nop 1
	v_mov_b32_e32 v146, 0
	s_and_saveexec_b64 s[38:39], vcc
	s_cbranch_execz .LBB0_930
	s_waitcnt lgkmcnt(0)
	v_add_f32_e32 v3, v3, v146
	v_fmamk_f32 v3, v3, 0x3c000000, v198
	s_mov_b32 s3, 0x800000
	v_cmp_gt_f32_e32 vcc, s3, v3
	v_mul_f32_e32 v132, 0x4b800000, v3
	v_lshlrev_b32_e32 v146, 16, v88
	v_cndmask_b32_e32 v3, v3, v132, vcc
	v_rsq_f32_e32 v3, v3
	v_and_b32_e32 v147, 0xffff0000, v88
	v_lshlrev_b32_e32 v88, 16, v89
	v_and_b32_e32 v89, 0xffff0000, v89
	v_mul_f32_e32 v132, 0x45800000, v3
	v_cndmask_b32_e32 v132, v3, v132, vcc
	v_mul_f32_e32 v3, 0xbfb8aa3b, v146
	v_exp_f32_e32 v3, v3
	v_pk_mul_f32 v[128:129], v[128:129], v[132:133] op_sel_hi:[1,0]
	v_pk_mul_f32 v[126:127], v[126:127], v[132:133] op_sel_hi:[1,0]
	v_pk_mul_f32 v[128:129], v[72:73], v[128:129]
	v_add_f32_e32 v3, 1.0, v3
	v_rcp_f32_e32 v148, v3
	v_mul_f32_e32 v3, 0xbfb8aa3b, v147
	v_exp_f32_e32 v3, v3
	v_pk_mul_f32 v[126:127], v[74:75], v[126:127]
	v_pk_mul_f32 v[122:123], v[122:123], v[132:133] op_sel_hi:[1,0]
	s_add_i32 s3, s43, s25
	v_add_f32_e32 v3, 1.0, v3
	v_rcp_f32_e32 v149, v3
	v_mul_f32_e32 v3, 0xbfb8aa3b, v88
	v_exp_f32_e32 v3, v3
	v_pk_mul_f32 v[122:123], v[68:69], v[122:123]
	v_pk_mul_f32 v[146:147], v[148:149], v[146:147]
	v_pk_mul_f32 v[0:1], v[0:1], v[132:133] op_sel_hi:[1,0]
	v_add_f32_e32 v3, 1.0, v3
	v_pk_mul_f32 v[128:129], v[146:147], v[128:129]
	v_rcp_f32_e32 v146, v3
	v_mul_f32_e32 v3, 0xbfb8aa3b, v89
	v_exp_f32_e32 v3, v3
	v_add_u32_e32 v134, s3, v145
	v_pk_mul_f32 v[0:1], v[70:71], v[0:1]
	v_ashrrev_i32_e32 v135, 31, v134
	v_add_f32_e32 v3, 1.0, v3
	v_rcp_f32_e32 v147, v3
	s_nop 0
	v_pk_mul_f32 v[88:89], v[146:147], v[88:89]
	s_nop 0
	v_pk_mul_f32 v[126:127], v[88:89], v[126:127]
	v_lshlrev_b32_e32 v88, 16, v90
	v_mul_f32_e32 v3, 0xbfb8aa3b, v88
	v_exp_f32_e32 v3, v3
	v_and_b32_e32 v89, 0xffff0000, v90
	v_add_f32_e32 v3, 1.0, v3
	v_rcp_f32_e32 v146, v3
	v_mul_f32_e32 v3, 0xbfb8aa3b, v89
	v_exp_f32_e32 v3, v3
	s_nop 0
	v_add_f32_e32 v3, 1.0, v3
	v_rcp_f32_e32 v147, v3
	s_nop 0
	v_pk_mul_f32 v[88:89], v[146:147], v[88:89]
	s_nop 0
	v_pk_mul_f32 v[122:123], v[88:89], v[122:123]
	v_lshlrev_b32_e32 v88, 16, v91
	v_mul_f32_e32 v3, 0xbfb8aa3b, v88
	v_exp_f32_e32 v3, v3
	v_and_b32_e32 v89, 0xffff0000, v91
	v_add_f32_e32 v3, 1.0, v3
	v_rcp_f32_e32 v90, v3
	v_mul_f32_e32 v3, 0xbfb8aa3b, v89
	v_exp_f32_e32 v3, v3
	s_nop 0
	v_add_f32_e32 v3, 1.0, v3
	v_rcp_f32_e32 v91, v3
	s_nop 0
	v_pk_mul_f32 v[88:89], v[90:91], v[88:89]
	s_nop 0
	v_pk_mul_f32 v[0:1], v[88:89], v[0:1]
	v_cvt_pk_bf16_f32 v90, v122, v123
	v_cvt_pk_bf16_f32 v91, v0, v1
	v_or_b32_e32 v0, s2, v140
	v_lshlrev_b64 v[122:123], 12, v[134:135]
	v_lshl_add_u64 v[122:123], s[80:81], 0, v[122:123]
	v_ashrrev_i32_e32 v1, 31, v0
	v_cvt_pk_bf16_f32 v88, v128, v129
	v_cvt_pk_bf16_f32 v89, v126, v127
	v_lshl_add_u64 v[0:1], v[0:1], 1, v[122:123]
	global_store_dwordx4 v[0:1], v[88:91], off
